# barrier 0 also uses the all-to-all XCD release (no top counter / generation flag round trip)
# speedup vs baseline: 1.0063x; 1.0046x over previous
.Lgb0_noclr:
	v_add_u32_e32 v253, 0x1000, v251
	v_add_u32_e32 v255, 0x2000, v251
	s_nop 0
	global_atomic_add v254, v253, v252, s[4:5] offset:1024 sc0
	s_waitcnt vmcnt(0)
	v_readfirstlane_b32 s10, v254
	s_nop 1
	s_add_u32 s10, s10, 1
	s_cmp_eq_u32 s10, s8
	s_cbranch_scc0 .Lgb0_follower
	buffer_wbl2 sc1
	s_waitcnt vmcnt(0)
	buffer_inv sc1
	v_mov_b32_e32 v254, 0x2400
	global_atomic_add v254, v252, s[4:5]
	global_atomic_add v254, v252, s[4:5] offset:256
	global_atomic_add v254, v252, s[4:5] offset:512
	global_atomic_add v254, v252, s[4:5] offset:768
	global_atomic_add v254, v252, s[4:5] offset:1024
	global_atomic_add v254, v252, s[4:5] offset:1280
	global_atomic_add v254, v252, s[4:5] offset:1536
	global_atomic_add v254, v252, s[4:5] offset:1792
	s_branch .Lgb0_fwait
.Lgb0_follower:
	buffer_inv sc1
.Lgb0_fwait:
	s_movk_i32 s11, 0x4000
.Lgb0_fspin:
	global_load_dword v254, v255, s[4:5] offset:1024 sc1
	s_waitcnt vmcnt(0)
	v_readfirstlane_b32 s10, v254
	s_nop 1
	s_cmp_ge_u32 s10, s9
	s_cbranch_scc1 .Lgb0_fdone
	s_sleep 1
	s_sub_u32 s11, s11, 1
	s_cmp_lg_u32 s11, 0
	s_cbranch_scc1 .Lgb0_fspin

.LBB0_127:
	s_waitcnt vmcnt(0)
	s_barrier
	s_mov_b64 s[2:3], exec
	v_readlane_b32 s4, v248, 7
	v_readlane_b32 s5, v248, 8
	s_and_b64 s[4:5], s[2:3], s[4:5]
	s_mov_b64 exec, s[4:5]
	s_cbranch_execz .LBB0_179
	v_readlane_b32 s4, v248, 4
	v_readlane_b32 s5, v248, 5
	v_readlane_b32 s8, v248, 6
	v_readlane_b32 s9, v249, 14
	v_readlane_b32 s10, v249, 15
	v_mov_b32_e32 v1, 1
	v_mov_b32_e32 v3, 0x3400
	s_nop 1
	s_lshl_b32 s8, s8, 8
	s_mul_i32 s9, s9, 2
	s_mul_i32 s10, s10, 2
	v_mov_b32_e32 v0, s8
	v_add_u32_e32 v2, 0x1000, v0
	v_add_u32_e32 v4, 0x2000, v0
	s_nop 1
	global_atomic_add v5, v2, v1, s[4:5] offset:1024 sc0
	s_waitcnt vmcnt(0)
	v_readfirstlane_b32 s11, v5
	s_nop 1
	s_add_u32 s11, s11, 1
	s_cmp_eq_u32 s11, s9
	s_cbranch_scc0 .Lhb1_follower
	buffer_wbl2 sc1
	s_waitcnt vmcnt(0)
	buffer_inv sc1
	v_mov_b32_e32 v5, 0x2400
	global_atomic_add v5, v1, s[4:5]
	global_atomic_add v5, v1, s[4:5] offset:256
	global_atomic_add v5, v1, s[4:5] offset:512
	global_atomic_add v5, v1, s[4:5] offset:768
	global_atomic_add v5, v1, s[4:5] offset:1024
	global_atomic_add v5, v1, s[4:5] offset:1280
	global_atomic_add v5, v1, s[4:5] offset:1536
	global_atomic_add v5, v1, s[4:5] offset:1792
	s_branch .Lhb1_fwait

.LBB0_309:
	s_waitcnt vmcnt(0)
	s_barrier
	s_mov_b64 s[2:3], exec
	v_readlane_b32 s4, v248, 7
	v_readlane_b32 s5, v248, 8
	s_and_b64 s[4:5], s[2:3], s[4:5]
	s_mov_b64 exec, s[4:5]
	s_cbranch_execz .LBB0_361
	v_readlane_b32 s4, v248, 4
	v_readlane_b32 s5, v248, 5
	v_readlane_b32 s8, v248, 6
	v_readlane_b32 s9, v249, 14
	v_readlane_b32 s10, v249, 15
	v_mov_b32_e32 v1, 1
	v_mov_b32_e32 v3, 0x3400
	s_nop 1
	s_lshl_b32 s8, s8, 8
	s_mul_i32 s9, s9, 3
	s_mul_i32 s10, s10, 3
	v_mov_b32_e32 v0, s8
	v_add_u32_e32 v2, 0x1000, v0
	v_add_u32_e32 v4, 0x2000, v0
	s_nop 1
	global_atomic_add v5, v2, v1, s[4:5] offset:1024 sc0
	s_waitcnt vmcnt(0)
	v_readfirstlane_b32 s11, v5
	s_nop 1
	s_add_u32 s11, s11, 1
	s_cmp_eq_u32 s11, s9
	s_cbranch_scc0 .Lhb2_follower
	buffer_wbl2 sc1
	s_waitcnt vmcnt(0)
	buffer_inv sc1
	v_mov_b32_e32 v5, 0x2400
	global_atomic_add v5, v1, s[4:5]
	global_atomic_add v5, v1, s[4:5] offset:256
	global_atomic_add v5, v1, s[4:5] offset:512
	global_atomic_add v5, v1, s[4:5] offset:768
	global_atomic_add v5, v1, s[4:5] offset:1024
	global_atomic_add v5, v1, s[4:5] offset:1280
	global_atomic_add v5, v1, s[4:5] offset:1536
	global_atomic_add v5, v1, s[4:5] offset:1792
	s_branch .Lhb2_fwait

.LBB0_616:
	s_waitcnt vmcnt(0)
	s_barrier
	s_mov_b64 s[2:3], exec
	v_readlane_b32 s4, v248, 7
	v_readlane_b32 s5, v248, 8
	s_and_b64 s[4:5], s[2:3], s[4:5]
	s_mov_b64 exec, s[4:5]
	s_cbranch_execz .LBB0_668
	v_readlane_b32 s4, v248, 4
	v_readlane_b32 s5, v248, 5
	v_readlane_b32 s8, v248, 6
	v_readlane_b32 s9, v249, 14
	v_readlane_b32 s10, v249, 15
	v_mov_b32_e32 v1, 1
	v_mov_b32_e32 v3, 0x3400
	s_nop 1
	s_lshl_b32 s8, s8, 8
	s_mul_i32 s9, s9, 4
	s_mul_i32 s10, s10, 4
	v_mov_b32_e32 v0, s8
	v_add_u32_e32 v2, 0x1000, v0
	v_add_u32_e32 v4, 0x2000, v0
	s_nop 1
	global_atomic_add v5, v2, v1, s[4:5] offset:1024 sc0
	s_waitcnt vmcnt(0)
	v_readfirstlane_b32 s11, v5
	s_nop 1
	s_add_u32 s11, s11, 1
	s_cmp_eq_u32 s11, s9
	s_cbranch_scc0 .Lhb3_follower
	buffer_wbl2 sc1
	s_waitcnt vmcnt(0)
	buffer_inv sc1
	v_mov_b32_e32 v5, 0x2400
	global_atomic_add v5, v1, s[4:5]
	global_atomic_add v5, v1, s[4:5] offset:256
	global_atomic_add v5, v1, s[4:5] offset:512
	global_atomic_add v5, v1, s[4:5] offset:768
	global_atomic_add v5, v1, s[4:5] offset:1024
	global_atomic_add v5, v1, s[4:5] offset:1280
	global_atomic_add v5, v1, s[4:5] offset:1536
	global_atomic_add v5, v1, s[4:5] offset:1792
	s_branch .Lhb3_fwait

.LBB0_686:
	s_waitcnt vmcnt(0)
	s_waitcnt vmcnt(63) expcnt(7) lgkmcnt(15)
	s_barrier
	s_mov_b64 s[2:3], exec
	v_readlane_b32 s4, v248, 7
	v_readlane_b32 s5, v248, 8
	s_and_b64 s[4:5], s[2:3], s[4:5]
	s_mov_b64 exec, s[4:5]
	s_cbranch_execz .LBB0_738
	v_readlane_b32 s4, v248, 4
	v_readlane_b32 s5, v248, 5
	v_readlane_b32 s8, v248, 6
	v_readlane_b32 s9, v249, 14
	v_readlane_b32 s10, v249, 15
	v_mov_b32_e32 v1, 1
	v_mov_b32_e32 v3, 0x3400
	s_nop 1
	s_lshl_b32 s8, s8, 8
	s_mul_i32 s9, s9, 5
	s_mul_i32 s10, s10, 5
	v_mov_b32_e32 v0, s8
	v_add_u32_e32 v2, 0x1000, v0
	v_add_u32_e32 v4, 0x2000, v0
	s_nop 1
	global_atomic_add v5, v2, v1, s[4:5] offset:1024 sc0
	s_waitcnt vmcnt(0)
	v_readfirstlane_b32 s11, v5
	s_nop 1
	s_add_u32 s11, s11, 1
	s_cmp_eq_u32 s11, s9
	s_cbranch_scc0 .Lhb4_follower
	buffer_wbl2 sc1
	s_waitcnt vmcnt(0)
	buffer_inv sc1
	v_mov_b32_e32 v5, 0x2400
	global_atomic_add v5, v1, s[4:5]
	global_atomic_add v5, v1, s[4:5] offset:256
	global_atomic_add v5, v1, s[4:5] offset:512
	global_atomic_add v5, v1, s[4:5] offset:768
	global_atomic_add v5, v1, s[4:5] offset:1024
	global_atomic_add v5, v1, s[4:5] offset:1280
	global_atomic_add v5, v1, s[4:5] offset:1536
	global_atomic_add v5, v1, s[4:5] offset:1792
	s_branch .Lhb4_fwait

.LBB0_819:
	s_waitcnt vmcnt(0)
	s_barrier
	s_mov_b64 s[2:3], exec
	v_readlane_b32 s4, v248, 7
	v_readlane_b32 s5, v248, 8
	s_and_b64 s[4:5], s[2:3], s[4:5]
	s_mov_b64 exec, s[4:5]
	s_cbranch_execz .LBB0_871
	v_readlane_b32 s4, v248, 4
	v_readlane_b32 s5, v248, 5
	v_readlane_b32 s8, v248, 6
	v_readlane_b32 s9, v249, 14
	v_readlane_b32 s10, v249, 15
	v_mov_b32_e32 v1, 1
	v_mov_b32_e32 v3, 0x3400
	s_nop 1
	s_lshl_b32 s8, s8, 8
	s_mul_i32 s9, s9, 6
	s_mul_i32 s10, s10, 6
	v_mov_b32_e32 v0, s8
	v_add_u32_e32 v2, 0x1000, v0
	v_add_u32_e32 v4, 0x2000, v0
	s_nop 1
	global_atomic_add v5, v2, v1, s[4:5] offset:1024 sc0
	s_waitcnt vmcnt(0)
	v_readfirstlane_b32 s11, v5
	s_nop 1
	s_add_u32 s11, s11, 1
	s_cmp_eq_u32 s11, s9
	s_cbranch_scc0 .Lhb5_follower
	buffer_wbl2 sc1
	s_waitcnt vmcnt(0)
	buffer_inv sc1
	v_mov_b32_e32 v5, 0x2400
	global_atomic_add v5, v1, s[4:5]
	global_atomic_add v5, v1, s[4:5] offset:256
	global_atomic_add v5, v1, s[4:5] offset:512
	global_atomic_add v5, v1, s[4:5] offset:768
	global_atomic_add v5, v1, s[4:5] offset:1024
	global_atomic_add v5, v1, s[4:5] offset:1280
	global_atomic_add v5, v1, s[4:5] offset:1536
	global_atomic_add v5, v1, s[4:5] offset:1792
	s_branch .Lhb5_fwait

.LBB0_904:
	s_waitcnt vmcnt(0)
	s_barrier
	s_mov_b64 s[2:3], exec
	v_readlane_b32 s4, v248, 7
	v_readlane_b32 s5, v248, 8
	s_and_b64 s[4:5], s[2:3], s[4:5]
	s_mov_b64 exec, s[4:5]
	s_cbranch_execz .LBB0_956
	v_readlane_b32 s4, v248, 4
	v_readlane_b32 s5, v248, 5
	v_readlane_b32 s8, v248, 6
	v_readlane_b32 s9, v249, 14
	v_readlane_b32 s10, v249, 15
	v_mov_b32_e32 v1, 1
	v_mov_b32_e32 v3, 0x3400
	s_nop 1
	s_lshl_b32 s8, s8, 8
	s_mul_i32 s9, s9, 7
	s_mul_i32 s10, s10, 7
	v_mov_b32_e32 v0, s8
	v_add_u32_e32 v2, 0x1000, v0
	v_add_u32_e32 v4, 0x2000, v0
	s_nop 1
	global_atomic_add v5, v2, v1, s[4:5] offset:1024 sc0
	s_waitcnt vmcnt(0)
	v_readfirstlane_b32 s11, v5
	s_nop 1
	s_add_u32 s11, s11, 1
	s_cmp_eq_u32 s11, s9
	s_cbranch_scc0 .Lhb6_follower
	buffer_wbl2 sc1
	s_waitcnt vmcnt(0)
	buffer_inv sc1
	v_mov_b32_e32 v5, 0x2400
	global_atomic_add v5, v1, s[4:5]
	global_atomic_add v5, v1, s[4:5] offset:256
	global_atomic_add v5, v1, s[4:5] offset:512
	global_atomic_add v5, v1, s[4:5] offset:768
	global_atomic_add v5, v1, s[4:5] offset:1024
	global_atomic_add v5, v1, s[4:5] offset:1280
	global_atomic_add v5, v1, s[4:5] offset:1536
	global_atomic_add v5, v1, s[4:5] offset:1792
	s_branch .Lhb6_fwait

.LBB0_1019:
	s_waitcnt vmcnt(0)
	s_barrier
	s_mov_b64 s[2:3], exec
	v_readlane_b32 s4, v248, 7
	v_readlane_b32 s5, v248, 8
	s_and_b64 s[4:5], s[2:3], s[4:5]
	s_mov_b64 exec, s[4:5]
	s_cbranch_execz .LBB0_1071
	v_readlane_b32 s4, v248, 4
	v_readlane_b32 s5, v248, 5
	v_readlane_b32 s8, v248, 6
	v_readlane_b32 s9, v249, 14
	v_readlane_b32 s10, v249, 15
	v_mov_b32_e32 v1, 1
	v_mov_b32_e32 v3, 0x3400
	s_nop 1
	s_lshl_b32 s8, s8, 8
	s_mul_i32 s9, s9, 8
	s_mul_i32 s10, s10, 8
	v_mov_b32_e32 v0, s8
	v_add_u32_e32 v2, 0x1000, v0
	v_add_u32_e32 v4, 0x2000, v0
	s_nop 1
	global_atomic_add v5, v2, v1, s[4:5] offset:1024 sc0
	s_waitcnt vmcnt(0)
	v_readfirstlane_b32 s11, v5
	s_nop 1
	s_add_u32 s11, s11, 1
	s_cmp_eq_u32 s11, s9
	s_cbranch_scc0 .Lhb7_follower
	buffer_wbl2 sc1
	s_waitcnt vmcnt(0)
	buffer_inv sc1
	v_mov_b32_e32 v5, 0x2400
	global_atomic_add v5, v1, s[4:5]
	global_atomic_add v5, v1, s[4:5] offset:256
	global_atomic_add v5, v1, s[4:5] offset:512
	global_atomic_add v5, v1, s[4:5] offset:768
	global_atomic_add v5, v1, s[4:5] offset:1024
	global_atomic_add v5, v1, s[4:5] offset:1280
	global_atomic_add v5, v1, s[4:5] offset:1536
	global_atomic_add v5, v1, s[4:5] offset:1792
	s_branch .Lhb7_fwait

.LBB0_1079:
	s_waitcnt vmcnt(0)
	s_barrier
	s_mov_b64 s[2:3], exec
	v_readlane_b32 s4, v248, 7
	v_readlane_b32 s5, v248, 8
	s_and_b64 s[4:5], s[2:3], s[4:5]
	s_mov_b64 exec, s[4:5]
	s_cbranch_execz .LBB0_1131
	v_readlane_b32 s4, v248, 4
	v_readlane_b32 s5, v248, 5
	v_readlane_b32 s8, v248, 6
	v_readlane_b32 s9, v249, 14
	v_readlane_b32 s10, v249, 15
	v_mov_b32_e32 v1, 1
	v_mov_b32_e32 v3, 0x3400
	s_nop 1
	s_lshl_b32 s8, s8, 8
	s_mul_i32 s9, s9, 9
	s_mul_i32 s10, s10, 9
	v_mov_b32_e32 v0, s8
	v_add_u32_e32 v2, 0x1000, v0
	v_add_u32_e32 v4, 0x2000, v0
	s_nop 1
	global_atomic_add v5, v2, v1, s[4:5] offset:1024 sc0
	s_waitcnt vmcnt(0)
	v_readfirstlane_b32 s11, v5
	s_nop 1
	s_add_u32 s11, s11, 1
	s_cmp_eq_u32 s11, s9
	s_cbranch_scc0 .Lhb8_follower
	buffer_wbl2 sc1
	s_waitcnt vmcnt(0)
	buffer_inv sc1
	v_mov_b32_e32 v5, 0x2400
	global_atomic_add v5, v1, s[4:5]
	global_atomic_add v5, v1, s[4:5] offset:256
	global_atomic_add v5, v1, s[4:5] offset:512
	global_atomic_add v5, v1, s[4:5] offset:768
	global_atomic_add v5, v1, s[4:5] offset:1024
	global_atomic_add v5, v1, s[4:5] offset:1280
	global_atomic_add v5, v1, s[4:5] offset:1536
	global_atomic_add v5, v1, s[4:5] offset:1792
	s_branch .Lhb8_fwait

.LBB0_1214:
	s_waitcnt vmcnt(0)
	s_barrier
	s_mov_b64 s[2:3], exec
	v_readlane_b32 s4, v248, 7
	v_readlane_b32 s5, v248, 8
	s_and_b64 s[4:5], s[2:3], s[4:5]
	s_mov_b64 exec, s[4:5]
	s_cbranch_execz .LBB0_1266
	v_readlane_b32 s4, v248, 4
	v_readlane_b32 s5, v248, 5
	v_readlane_b32 s8, v248, 6
	v_readlane_b32 s9, v249, 14
	v_readlane_b32 s10, v249, 15
	v_mov_b32_e32 v1, 1
	v_mov_b32_e32 v3, 0x3400
	s_nop 1
	s_lshl_b32 s8, s8, 8
	s_mul_i32 s9, s9, 10
	s_mul_i32 s10, s10, 10
	v_mov_b32_e32 v0, s8
	v_add_u32_e32 v2, 0x1000, v0
	v_add_u32_e32 v4, 0x2000, v0
	s_nop 1
	global_atomic_add v5, v2, v1, s[4:5] offset:1024 sc0
	s_waitcnt vmcnt(0)
	v_readfirstlane_b32 s11, v5
	s_nop 1
	s_add_u32 s11, s11, 1
	s_cmp_eq_u32 s11, s9
	s_cbranch_scc0 .Lhb9_follower
	buffer_wbl2 sc1
	s_waitcnt vmcnt(0)
	buffer_inv sc1
	v_mov_b32_e32 v5, 0x2400
	global_atomic_add v5, v1, s[4:5]
	global_atomic_add v5, v1, s[4:5] offset:256
	global_atomic_add v5, v1, s[4:5] offset:512
	global_atomic_add v5, v1, s[4:5] offset:768
	global_atomic_add v5, v1, s[4:5] offset:1024
	global_atomic_add v5, v1, s[4:5] offset:1280
	global_atomic_add v5, v1, s[4:5] offset:1536
	global_atomic_add v5, v1, s[4:5] offset:1792
	s_branch .Lhb9_fwait
